# grid-barrier spin polls with s_sleep 1 instead of 8 (about 0.3 us less per barrier)
# speedup vs baseline: 1.0010x; 1.0010x over previous
.LBB0_58:
	s_and_b32 s18, s22, 0xff
	s_mov_b64 s[16:17], -1
	s_cmp_lg_u32 s18, 0
	s_mov_b64 s[20:21], -1
	s_sleep 1
	s_cbranch_scc0 .LBB0_61
	s_and_b64 vcc, exec, s[20:21]
	s_cbranch_vccz .LBB0_57

.LBB0_75:
	s_and_b32 s20, s26, 0xff
	s_cmp_lg_u32 s20, 0
	s_mov_b64 s[22:23], -1
	s_sleep 1
	s_cbranch_scc0 .LBB0_78
	s_mov_b64 s[24:25], -1
	s_and_b64 vcc, exec, s[22:23]
	s_cbranch_vccz .LBB0_74

.LBB0_116:
	s_and_b32 s22, s26, 0xff
	s_mov_b64 s[20:21], -1
	s_cmp_lg_u32 s22, 0
	s_mov_b64 s[24:25], -1
	s_sleep 1
	s_cbranch_scc0 .LBB0_119
	s_and_b64 vcc, exec, s[24:25]
	s_cbranch_vccz .LBB0_115

.LBB0_133:
	s_and_b32 s22, s28, 0xff
	s_cmp_lg_u32 s22, 0
	s_mov_b64 s[24:25], -1
	s_sleep 1
	s_cbranch_scc0 .LBB0_136
	s_mov_b64 s[26:27], -1
	s_and_b64 vcc, exec, s[24:25]
	s_cbranch_vccz .LBB0_132

.LBB0_184:
	s_and_b32 s16, s20, 0xff
	s_mov_b64 s[14:15], -1
	s_cmp_lg_u32 s16, 0
	s_mov_b64 s[18:19], -1
	s_sleep 1
	s_cbranch_scc0 .LBB0_187
	s_and_b64 vcc, exec, s[18:19]
	s_cbranch_vccz .LBB0_183

.LBB0_201:
	s_and_b32 s18, s24, 0xff
	s_cmp_lg_u32 s18, 0
	s_mov_b64 s[20:21], -1
	s_sleep 1
	s_cbranch_scc0 .LBB0_204
	s_mov_b64 s[22:23], -1
	s_and_b64 vcc, exec, s[20:21]
	s_cbranch_vccz .LBB0_200

.LBB0_426:
	s_and_b32 s16, s22, 0xff
	s_cmp_lg_u32 s16, 0
	s_mov_b64 s[18:19], -1
	s_sleep 1
	s_cbranch_scc0 .LBB0_429
	s_mov_b64 s[20:21], -1
	s_and_b64 vcc, exec, s[18:19]
	s_cbranch_vccz .LBB0_425

.LBB0_469:
	s_and_b32 s20, s24, 0xff
	s_mov_b64 s[18:19], -1
	s_cmp_lg_u32 s20, 0
	s_mov_b64 s[22:23], -1
	s_sleep 1
	s_cbranch_scc0 .LBB0_472
	s_and_b64 vcc, exec, s[22:23]
	s_cbranch_vccz .LBB0_468

.LBB0_555:
	s_and_b32 s24, s28, 0xff
	s_mov_b64 s[22:23], -1
	s_cmp_lg_u32 s24, 0
	s_mov_b64 s[26:27], -1
	s_sleep 1
	s_cbranch_scc0 .LBB0_558
	s_and_b64 vcc, exec, s[26:27]
	s_cbranch_vccz .LBB0_554

.LBB0_572:
	s_and_b32 s26, s37, 0xff
	s_cmp_lg_u32 s26, 0
	s_mov_b64 s[28:29], -1
	s_sleep 1
	s_cbranch_scc0 .LBB0_575
	s_mov_b64 s[30:31], -1
	s_and_b64 vcc, exec, s[28:29]
	s_cbranch_vccz .LBB0_571
